# final write-out loop: 8 consecutive 1 KiB chunks per wave per step, grid sweeps one contiguous window
# baseline (speedup 1.0000x reference)
.LBB0_951:
	v_readlane_b32 s0, v255, 26
	v_readlane_b32 s1, v255, 27
	s_andn2_b64 vcc, exec, s[0:1]
	s_mov_b32 s35, 0x16000
	s_mov_b32 s54, 0xa000
	s_mov_b32 s55, 0xb000
	s_mov_b32 s56, 0x2a000
	s_mov_b32 s57, 0x2c000
	s_cbranch_vccnz .LBB0_957
	v_readlane_b32 s0, v255, 32
	s_cmp_eq_u32 s0, 0
	s_cbranch_scc0 .LBB0_957
	s_ashr_i32 s47, s46, 31
	s_lshl_b64 s[0:1], s[46:47], 9
	s_waitcnt lgkmcnt(0)
	v_mov_b64_e32 v[0:1], 0x1ffffff
	v_cmp_gt_u64_e32 vcc, s[0:1], v[0:1]
	s_cbranch_vccnz .LBB0_957
	s_lshl_b64 s[4:5], s[46:47], 14
	s_add_u32 s4, s50, s4
	s_addc_u32 s5, s51, s5
	v_lshlrev_b32_e32 v96, 5, v246
	v_lshl_add_u64 v[2:3], s[4:5], 0, v[96:97]
	s_lshl_b64 s[6:7], s[46:47], 13
	s_add_u32 s6, s52, s6
	s_addc_u32 s7, s53, s7
	v_lshlrev_b32_e32 v96, 4, v246
	v_lshl_add_u64 v[4:5], s[6:7], 0, v[96:97]
	s_mov_b64 s[0:1], 0x1000
	s_mov_b64 s[24:25], 0x1000000
	s_mov_b64 s[4:5], 0x2000000
	s_mov_b32 s8, 4
.LBB0_955:
	global_load_dwordx4 v[6:9], v[4:5], off offset:0
	global_load_dwordx4 v[10:13], v[4:5], off offset:1024
	global_load_dwordx4 v[14:17], v[4:5], off offset:2048
	global_load_dwordx4 v[18:21], v[4:5], off offset:3072
	v_lshl_add_u64 v[0:1], v[4:5], 0, s[0:1]
	global_load_dwordx4 v[22:25], v[0:1], off offset:0
	global_load_dwordx4 v[26:29], v[0:1], off offset:1024
	global_load_dwordx4 v[30:33], v[0:1], off offset:2048
	global_load_dwordx4 v[34:37], v[0:1], off offset:3072
	v_lshl_add_u64 v[4:5], v[4:5], 0, s[24:25]
	v_mov_b64_e32 v[0:1], v[2:3]
	s_waitcnt vmcnt(7)
	v_lshlrev_b32_e32 v100, 16, v6
	v_and_b32_e32 v101, 0xffff0000, v6
	v_lshlrev_b32_e32 v102, 16, v7
	v_and_b32_e32 v103, 0xffff0000, v7
	v_lshlrev_b32_e32 v104, 16, v8
	v_and_b32_e32 v105, 0xffff0000, v8
	v_lshlrev_b32_e32 v106, 16, v9
	v_and_b32_e32 v107, 0xffff0000, v9
	global_store_dwordx4 v[0:1], v[100:103], off offset:0
	global_store_dwordx4 v[0:1], v[104:107], off offset:16
	s_waitcnt vmcnt(8)
	v_lshlrev_b32_e32 v108, 16, v10
	v_and_b32_e32 v109, 0xffff0000, v10
	v_lshlrev_b32_e32 v110, 16, v11
	v_and_b32_e32 v111, 0xffff0000, v11
	v_lshlrev_b32_e32 v112, 16, v12
	v_and_b32_e32 v113, 0xffff0000, v12
	v_lshlrev_b32_e32 v114, 16, v13
	v_and_b32_e32 v115, 0xffff0000, v13
	global_store_dwordx4 v[0:1], v[108:111], off offset:2048
	global_store_dwordx4 v[0:1], v[112:115], off offset:2064
	v_lshl_add_u64 v[0:1], v[0:1], 0, s[0:1]
	s_waitcnt vmcnt(9)
	v_lshlrev_b32_e32 v116, 16, v14
	v_and_b32_e32 v117, 0xffff0000, v14
	v_lshlrev_b32_e32 v118, 16, v15
	v_and_b32_e32 v119, 0xffff0000, v15
	v_lshlrev_b32_e32 v120, 16, v16
	v_and_b32_e32 v121, 0xffff0000, v16
	v_lshlrev_b32_e32 v122, 16, v17
	v_and_b32_e32 v123, 0xffff0000, v17
	global_store_dwordx4 v[0:1], v[116:119], off offset:0
	global_store_dwordx4 v[0:1], v[120:123], off offset:16
	s_waitcnt vmcnt(10)
	v_lshlrev_b32_e32 v124, 16, v18
	v_and_b32_e32 v125, 0xffff0000, v18
	v_lshlrev_b32_e32 v126, 16, v19
	v_and_b32_e32 v127, 0xffff0000, v19
	v_lshlrev_b32_e32 v128, 16, v20
	v_and_b32_e32 v129, 0xffff0000, v20
	v_lshlrev_b32_e32 v130, 16, v21
	v_and_b32_e32 v131, 0xffff0000, v21
	global_store_dwordx4 v[0:1], v[124:127], off offset:2048
	global_store_dwordx4 v[0:1], v[128:131], off offset:2064
	v_lshl_add_u64 v[0:1], v[0:1], 0, s[0:1]
	s_waitcnt vmcnt(11)
	v_lshlrev_b32_e32 v132, 16, v22
	v_and_b32_e32 v133, 0xffff0000, v22
	v_lshlrev_b32_e32 v134, 16, v23
	v_and_b32_e32 v135, 0xffff0000, v23
	v_lshlrev_b32_e32 v136, 16, v24
	v_and_b32_e32 v137, 0xffff0000, v24
	v_lshlrev_b32_e32 v138, 16, v25
	v_and_b32_e32 v139, 0xffff0000, v25
	global_store_dwordx4 v[0:1], v[132:135], off offset:0
	global_store_dwordx4 v[0:1], v[136:139], off offset:16
	s_waitcnt vmcnt(12)
	v_lshlrev_b32_e32 v140, 16, v26
	v_and_b32_e32 v141, 0xffff0000, v26
	v_lshlrev_b32_e32 v142, 16, v27
	v_and_b32_e32 v143, 0xffff0000, v27
	v_lshlrev_b32_e32 v144, 16, v28
	v_and_b32_e32 v145, 0xffff0000, v28
	v_lshlrev_b32_e32 v146, 16, v29
	v_and_b32_e32 v147, 0xffff0000, v29
	global_store_dwordx4 v[0:1], v[140:143], off offset:2048
	global_store_dwordx4 v[0:1], v[144:147], off offset:2064
	v_lshl_add_u64 v[0:1], v[0:1], 0, s[0:1]
	s_waitcnt vmcnt(13)
	v_lshlrev_b32_e32 v148, 16, v30
	v_and_b32_e32 v149, 0xffff0000, v30
	v_lshlrev_b32_e32 v150, 16, v31
	v_and_b32_e32 v151, 0xffff0000, v31
	v_lshlrev_b32_e32 v152, 16, v32
	v_and_b32_e32 v153, 0xffff0000, v32
	v_lshlrev_b32_e32 v154, 16, v33
	v_and_b32_e32 v155, 0xffff0000, v33
	global_store_dwordx4 v[0:1], v[148:151], off offset:0
	global_store_dwordx4 v[0:1], v[152:155], off offset:16
	s_waitcnt vmcnt(14)
	v_lshlrev_b32_e32 v156, 16, v34
	v_and_b32_e32 v157, 0xffff0000, v34
	v_lshlrev_b32_e32 v158, 16, v35
	v_and_b32_e32 v159, 0xffff0000, v35
	v_lshlrev_b32_e32 v160, 16, v36
	v_and_b32_e32 v161, 0xffff0000, v36
	v_lshlrev_b32_e32 v162, 16, v37
	v_and_b32_e32 v163, 0xffff0000, v37
	global_store_dwordx4 v[0:1], v[156:159], off offset:2048
	global_store_dwordx4 v[0:1], v[160:163], off offset:2064
	v_lshl_add_u64 v[2:3], v[2:3], 0, s[4:5]
	s_sub_i32 s8, s8, 1
	s_cmp_lg_u32 s8, 0
	s_cbranch_scc1 .LBB0_955
